# adds: rst (row rms factor) table entry computed inside the peeled first K-loop iteration's load-segment slack (waves 0-3, scratch VGPRs), removed from the epilogue's critical path
# baseline (speedup 1.0000x reference)
; #define PG8_STAGE(bufoff, gbase, voff) do { _Pragma("unroll") for (int _i = 0; _i < 2; ++_i) \
;         __builtin_amdgcn_global_load_lds((const unsigned*)((const char*)(gbase) + (size_t)_i * r64 + (voff)), (PG8_LAS unsigned*)(lds + (bufoff) + ldsw + _i * 8192), 16, 0, 0); } while (0)
; #define PG8_LDA(dst, b, h) do { _Pragma("unroll") for (int m = 0; m < 4; ++m) _Pragma("unroll") for (int k = 0; k < 2; ++k) dst[m][k] = *(const PG8_LAS bf16x8*)(lds + PG8_SA(b, h) + aoff + m * 2048 + k * 1024); } while (0)
; #define PG8_LDB(dst, b, h) do { _Pragma("unroll") for (int n = 0; n < 2; ++n) _Pragma("unroll") for (int k = 0; k < 2; ++k) dst[n][k] = *(const PG8_LAS bf16x8*)(lds + PG8_SB(b, h) + boff + n * 2048 + k * 1024); } while (0)
; #define PG8_MMA(ai, bj, At, Bt) do { __builtin_amdgcn_s_setprio(1); _Pragma("unroll") for (int m = 0; m < 4; ++m) _Pragma("unroll") for (int n = 0; n < 2; ++n) _Pragma("unroll") for (int k = 0; k < 2; ++k) \
;         acc[ai][bj][m][n] = __builtin_amdgcn_mfma_f32_16x16x32_bf16(Bt[n][k], At[m][k], acc[ai][bj][m][n], 0, 0, 0); __builtin_amdgcn_s_setprio(0); } while (0)
; #define PG8_WAIT_V(n) asm volatile("s_waitcnt vmcnt(" #n ")" ::: "memory")
; #define PG8_WAIT_L(n) asm volatile("s_waitcnt lgkmcnt(" #n ")" ::: "memory")
; #define PG8_BAR __builtin_amdgcn_s_barrier()
; #define PG8_SCHED __builtin_amdgcn_sched_barrier(0)
; template <class Epi, class Sched, bool ALIGN_EPI = false, bool SP2 = false>
; __device__ __forceinline__ void gemm_phase(PG8_LAS unsigned char* lds, const Gemm g, const Sched& S, const Epi& E) {
;     ...
;             PG8_LDB(B0, 0, 0); PG8_LDB(B1, 0, 1); PG8_SCHED; PG8_LDA(At, 0, 0); PG8_STAGE(PG8_SA(1, 1), a1 + hstep, voffA);
;             PG8_WAIT_V(8); PG8_WAIT_L(0); PG8_BAR; PG8_MMA(0, 0, At, B0); PG8_MMA(0, 1, At, B1); PG8_BAR; PG8_SCHED;
;             PG8_LDA(At, 0, 1); PG8_STAGE(PG8_SB(0, 0), b2, voffB); PG8_STAGE(PG8_SB(0, 1), b2 + hstep, voffB); PG8_STAGE(PG8_SA(0, 0), a2, voffA);
;             PG8_WAIT_V(8); PG8_WAIT_L(0); PG8_BAR; PG8_MMA(1, 0, At, B0); PG8_MMA(1, 1, At, B1); PG8_BAR; PG8_SCHED;
.LBB0_167:
	v_and_b32_e32 v2, 63, v214
	s_lshl_b32 s12, s45, 14
	s_lshl_b32 s3, s41, 1
	v_lshlrev_b32_e32 v2, 4, v2
	s_add_u32 s12, s12, s3
	s_add_u32 s12, s64, s12
	s_addc_u32 s13, s65, 0
	s_add_i32 m0, s3, 0x21000
	s_nop 0
	global_load_lds_dwordx4 v2, s[12:13]
	global_load_lds_dwordx4 v2, s[12:13] offset:1024
	s_add_u32 s6, s10, 0x80
	s_addc_u32 s7, s11, 0
	s_add_u32 s10, s8, 0x100
	s_addc_u32 s11, s9, 0
	s_mov_b32 s8, 0
	s_add_i32 s12, s8, 2
	s_add_u32 s3, s6, 0x80
	s_addc_u32 s9, s7, 0
	s_add_i32 s13, 0, 0x10000
	s_cmp_eq_u32 s70, s8
	s_cselect_b32 s9, s93, s9
	s_cselect_b32 s8, s92, s3
	s_cselect_b32 s19, s95, s11
	s_cselect_b32 s18, s94, s10
	s_add_i32 s3, 0, 0x14000
	v_add_u32_e32 v14, s13, v242
	v_add_u32_e32 v30, s3, v242
	s_waitcnt lgkmcnt(0)
	ds_read_b128 v[2:5], v14
	ds_read_b128 v[6:9], v14 offset:1024
	ds_read_b128 v[10:13], v14 offset:2048
	ds_read_b128 v[14:17], v14 offset:3072
	ds_read_b128 v[18:21], v30
	ds_read_b128 v[22:25], v30 offset:1024
	ds_read_b128 v[26:29], v30 offset:2048
	ds_read_b128 v[30:33], v30 offset:3072
	v_lshl_add_u64 v[194:195], s[6:7], 0, v[218:219]
	s_add_i32 m0, s90, 0xc000
	ds_read_b128 v[34:37], v243
	ds_read_b128 v[38:41], v243 offset:1024
	ds_read_b128 v[42:45], v243 offset:2048
	ds_read_b128 v[46:49], v243 offset:3072
	ds_read_b128 v[50:53], v243 offset:4096
	ds_read_b128 v[54:57], v243 offset:5120
	ds_read_b128 v[58:61], v243 offset:6144
	ds_read_b128 v[62:65], v243 offset:7168
	global_load_lds_dwordx4 v[194:195], off
	v_lshl_add_u64 v[194:195], s[6:7], 0, v[220:221]
	s_add_i32 m0, s90, 0xe000
	s_nop 0
	global_load_lds_dwordx4 v[194:195], off
	s_waitcnt vmcnt(8)
	s_waitcnt lgkmcnt(0)
	s_barrier
	s_setprio 1
	s_waitcnt lgkmcnt(0)
	v_mfma_f32_16x16x32_bf16 v[190:193], v[2:5], v[34:37], 0
	v_mfma_f32_16x16x32_bf16 v[186:189], v[10:13], v[34:37], 0
	v_mfma_f32_16x16x32_bf16 v[174:177], v[2:5], v[42:45], 0
	v_mfma_f32_16x16x32_bf16 v[170:173], v[10:13], v[42:45], 0
	v_mfma_f32_16x16x32_bf16 v[158:161], v[2:5], v[50:53], 0
	v_mfma_f32_16x16x32_bf16 v[154:157], v[10:13], v[50:53], 0
	v_mfma_f32_16x16x32_bf16 v[142:145], v[2:5], v[58:61], 0
	v_mfma_f32_16x16x32_bf16 v[138:141], v[10:13], v[58:61], 0
	v_mfma_f32_16x16x32_bf16 v[190:193], v[6:9], v[38:41], v[190:193]
	v_mfma_f32_16x16x32_bf16 v[186:189], v[14:17], v[38:41], v[186:189]
	v_mfma_f32_16x16x32_bf16 v[174:177], v[6:9], v[46:49], v[174:177]
	v_mfma_f32_16x16x32_bf16 v[170:173], v[14:17], v[46:49], v[170:173]
	v_mfma_f32_16x16x32_bf16 v[158:161], v[6:9], v[54:57], v[158:161]
	v_mfma_f32_16x16x32_bf16 v[154:157], v[14:17], v[54:57], v[154:157]
	v_mfma_f32_16x16x32_bf16 v[142:145], v[6:9], v[62:65], v[142:145]
	v_mfma_f32_16x16x32_bf16 v[138:141], v[14:17], v[62:65], v[138:141]
	s_setprio 0
	s_setprio 1
	v_mfma_f32_16x16x32_bf16 v[182:185], v[18:21], v[34:37], 0
	v_mfma_f32_16x16x32_bf16 v[34:37], v[26:29], v[34:37], 0
	v_mfma_f32_16x16x32_bf16 v[182:185], v[22:25], v[38:41], v[182:185]
	v_mfma_f32_16x16x32_bf16 v[34:37], v[30:33], v[38:41], v[34:37]
	v_mfma_f32_16x16x32_bf16 v[38:41], v[18:21], v[42:45], 0
	v_mfma_f32_16x16x32_bf16 v[42:45], v[26:29], v[42:45], 0
	v_mfma_f32_16x16x32_bf16 v[38:41], v[22:25], v[46:49], v[38:41]
	v_mfma_f32_16x16x32_bf16 v[42:45], v[30:33], v[46:49], v[42:45]
	v_mfma_f32_16x16x32_bf16 v[46:49], v[18:21], v[50:53], 0
	v_mfma_f32_16x16x32_bf16 v[50:53], v[26:29], v[50:53], 0
	v_mfma_f32_16x16x32_bf16 v[46:49], v[22:25], v[54:57], v[46:49]
	v_mfma_f32_16x16x32_bf16 v[50:53], v[30:33], v[54:57], v[50:53]
	v_mfma_f32_16x16x32_bf16 v[54:57], v[18:21], v[58:61], 0
	v_mfma_f32_16x16x32_bf16 v[58:61], v[26:29], v[58:61], 0
	v_mfma_f32_16x16x32_bf16 v[54:57], v[22:25], v[62:65], v[54:57]
	v_mfma_f32_16x16x32_bf16 v[58:61], v[30:33], v[62:65], v[58:61]
	s_setprio 0
	s_barrier
	s_add_i32 s13, s13, s41
	v_lshl_add_u64 v[228:229], s[18:19], 0, v[0:1]
	s_mov_b32 m0, s13
	ds_read_b128 v[62:65], v243 offset:16384
	ds_read_b128 v[130:133], v243 offset:17408
	ds_read_b128 v[134:137], v243 offset:18432
	ds_read_b128 v[146:149], v243 offset:19456
	ds_read_b128 v[150:153], v243 offset:20480
	ds_read_b128 v[162:165], v243 offset:21504
	ds_read_b128 v[166:169], v243 offset:22528
	ds_read_b128 v[178:181], v243 offset:23552
	global_load_lds_dwordx4 v[228:229], off
	s_add_i32 m0, s13, 0x2000
	s_add_u32 s18, s18, s58
	v_lshl_add_u64 v[230:231], v[228:229], 0, s[56:57]
	s_addc_u32 s19, s19, s59
	s_add_i32 s3, s3, s41
	global_load_lds_dwordx4 v[230:231], off
	v_lshl_add_u64 v[244:245], s[18:19], 0, v[0:1]
	s_mov_b32 m0, s3
	v_lshl_add_u64 v[246:247], v[244:245], 0, s[56:57]
	global_load_lds_dwordx4 v[244:245], off
	s_add_i32 m0, s3, 0x2000
	v_lshl_add_u64 v[248:249], s[8:9], 0, v[216:217]
	global_load_lds_dwordx4 v[246:247], off
	s_mov_b32 m0, s90
	v_lshl_add_u64 v[250:251], v[248:249], 0, s[56:57]
	global_load_lds_dwordx4 v[248:249], off
	s_mov_b32 m0, s91
	s_nop 0
	global_load_lds_dwordx4 v[250:251], off
	s_waitcnt vmcnt(8)
	s_waitcnt lgkmcnt(0)
	s_barrier
; #define PG8_STAGE(bufoff, gbase, voff) do { _Pragma("unroll") for (int _i = 0; _i < 2; ++_i) \
;         __builtin_amdgcn_global_load_lds((const unsigned*)((const char*)(gbase) + (size_t)_i * r64 + (voff)), (PG8_LAS unsigned*)(lds + (bufoff) + ldsw + _i * 8192), 16, 0, 0); } while (0)
; #define PG8_LDA(dst, b, h) do { _Pragma("unroll") for (int m = 0; m < 4; ++m) _Pragma("unroll") for (int k = 0; k < 2; ++k) dst[m][k] = *(const PG8_LAS bf16x8*)(lds + PG8_SA(b, h) + aoff + m * 2048 + k * 1024); } while (0)
; #define PG8_LDB(dst, b, h) do { _Pragma("unroll") for (int n = 0; n < 2; ++n) _Pragma("unroll") for (int k = 0; k < 2; ++k) dst[n][k] = *(const PG8_LAS bf16x8*)(lds + PG8_SB(b, h) + boff + n * 2048 + k * 1024); } while (0)
; #define PG8_MMA(ai, bj, At, Bt) do { __builtin_amdgcn_s_setprio(1); _Pragma("unroll") for (int m = 0; m < 4; ++m) _Pragma("unroll") for (int n = 0; n < 2; ++n) _Pragma("unroll") for (int k = 0; k < 2; ++k) \
;         acc[ai][bj][m][n] = __builtin_amdgcn_mfma_f32_16x16x32_bf16(Bt[n][k], At[m][k], acc[ai][bj][m][n], 0, 0, 0); __builtin_amdgcn_s_setprio(0); } while (0)
; #define PG8_WAIT_V(n) asm volatile("s_waitcnt vmcnt(" #n ")" ::: "memory")
; #define PG8_WAIT_L(n) asm volatile("s_waitcnt lgkmcnt(" #n ")" ::: "memory")
; #define PG8_BAR __builtin_amdgcn_s_barrier()
; #define PG8_SCHED __builtin_amdgcn_sched_barrier(0)
; template <class Epi, class Sched, bool ALIGN_EPI = false, bool SP2 = false>
; __device__ __forceinline__ void gemm_phase(PG8_LAS unsigned char* lds, const Gemm g, const Sched& S, const Epi& E) {
;     ...
;             PG8_LDA(At, 0, 1); PG8_STAGE(PG8_SB(0, 0), b2, voffB); PG8_STAGE(PG8_SB(0, 1), b2 + hstep, voffB); PG8_STAGE(PG8_SA(0, 0), a2, voffA);
;             PG8_WAIT_V(8); PG8_WAIT_L(0); PG8_BAR; PG8_MMA(1, 0, At, B0); PG8_MMA(1, 1, At, B1); PG8_BAR; PG8_SCHED;
;             PG8_LDB(B0, 1, 0); PG8_LDB(B1, 1, 1); PG8_SCHED; PG8_LDA(At, 1, 0); PG8_STAGE(PG8_SA(0, 1), a2 + hstep, voffA);
; __device__ __forceinline__ float row_rs(const float* rsp, int row) {
;     const f32x4* q = (const f32x4*)(rsp + (size_t)row * 16);
;     const f32x4 a = q[0], b = q[1], c = q[2], d = q[3];
;     const float s = ((a[0] + a[1]) + (a[2] + a[3])) + ((b[0] + b[1]) + (b[2] + b[3])) + ((c[0] + c[1]) + (c[2] + c[3])) + ((d[0] + d[1]) + (d[2] + d[3]));
	s_setprio 1
	s_waitcnt lgkmcnt(0)
	v_mfma_f32_16x16x32_bf16 v[126:129], v[2:5], v[62:65], 0
	v_mfma_f32_16x16x32_bf16 v[122:125], v[10:13], v[62:65], 0
	v_mfma_f32_16x16x32_bf16 v[110:113], v[2:5], v[134:137], 0
	v_mfma_f32_16x16x32_bf16 v[106:109], v[10:13], v[134:137], 0
	v_mfma_f32_16x16x32_bf16 v[94:97], v[2:5], v[150:153], 0
	v_mfma_f32_16x16x32_bf16 v[90:93], v[10:13], v[150:153], 0
	v_mfma_f32_16x16x32_bf16 v[2:5], v[2:5], v[166:169], 0
	v_mfma_f32_16x16x32_bf16 v[126:129], v[6:9], v[130:133], v[126:129]
	v_mfma_f32_16x16x32_bf16 v[122:125], v[14:17], v[130:133], v[122:125]
	v_mfma_f32_16x16x32_bf16 v[110:113], v[6:9], v[146:149], v[110:113]
	v_mfma_f32_16x16x32_bf16 v[106:109], v[14:17], v[146:149], v[106:109]
	v_mfma_f32_16x16x32_bf16 v[94:97], v[6:9], v[162:165], v[94:97]
	v_mfma_f32_16x16x32_bf16 v[90:93], v[14:17], v[162:165], v[90:93]
	v_mfma_f32_16x16x32_bf16 v[2:5], v[6:9], v[178:181], v[2:5]
	v_mfma_f32_16x16x32_bf16 v[6:9], v[10:13], v[166:169], 0
	v_mfma_f32_16x16x32_bf16 v[6:9], v[14:17], v[178:181], v[6:9]
	s_setprio 0
	s_setprio 1
	v_mfma_f32_16x16x32_bf16 v[74:77], v[26:29], v[134:137], 0
	v_mfma_f32_16x16x32_bf16 v[98:101], v[30:33], v[146:149], v[74:77]
	v_mfma_f32_16x16x32_bf16 v[74:77], v[18:21], v[150:153], 0
	v_mfma_f32_16x16x32_bf16 v[10:13], v[18:21], v[62:65], 0
	v_mfma_f32_16x16x32_bf16 v[14:17], v[26:29], v[62:65], 0
	v_mfma_f32_16x16x32_bf16 v[62:65], v[18:21], v[134:137], 0
	v_mfma_f32_16x16x32_bf16 v[86:89], v[22:25], v[162:165], v[74:77]
	v_mfma_f32_16x16x32_bf16 v[74:77], v[26:29], v[150:153], 0
	v_mfma_f32_16x16x32_bf16 v[18:21], v[18:21], v[166:169], 0
	v_mfma_f32_16x16x32_bf16 v[10:13], v[22:25], v[130:133], v[10:13]
	v_mfma_f32_16x16x32_bf16 v[62:65], v[22:25], v[146:149], v[62:65]
	v_mfma_f32_16x16x32_bf16 v[82:85], v[30:33], v[162:165], v[74:77]
	v_mfma_f32_16x16x32_bf16 v[18:21], v[22:25], v[178:181], v[18:21]
	v_mfma_f32_16x16x32_bf16 v[22:25], v[26:29], v[166:169], 0
	v_mfma_f32_16x16x32_bf16 v[14:17], v[30:33], v[130:133], v[14:17]
	v_mfma_f32_16x16x32_bf16 v[22:25], v[30:33], v[178:181], v[22:25]
	s_setprio 0
	s_barrier
	s_add_i32 s3, 0, 0x18000
	s_add_i32 s13, 0, 0x1c000
	v_add_u32_e32 v70, s3, v242
	v_add_u32_e32 v74, s13, v242
	ds_read_b128 v[26:29], v70
	ds_read_b128 v[30:33], v70 offset:1024
	ds_read_b128 v[66:69], v70 offset:2048
	ds_read_b128 v[70:73], v70 offset:3072
	ds_read_b128 v[194:197], v74
	ds_read_b128 v[198:201], v74 offset:1024
	ds_read_b128 v[202:205], v74 offset:2048
	ds_read_b128 v[206:209], v74 offset:3072
	s_add_u32 s8, s8, s58
	s_addc_u32 s9, s9, s59
	s_mov_b32 m0, s36
	v_lshl_add_u64 v[134:135], s[8:9], 0, v[216:217]
	ds_read_b128 v[74:77], v243 offset:32768
	ds_read_b128 v[78:81], v243 offset:33792
	ds_read_b128 v[102:105], v243 offset:34816
	ds_read_b128 v[114:117], v243 offset:35840
	ds_read_b128 v[118:121], v243 offset:36864
	ds_read_b128 v[130:133], v243 offset:37888
	ds_read_b128 v[210:213], v243 offset:38912
	ds_read_b128 v[224:227], v243 offset:39936
	global_load_lds_dwordx4 v[134:135], off
	v_lshl_add_u64 v[134:135], v[134:135], 0, s[56:57]
	s_mov_b32 m0, s62
	s_nop 0
	global_load_lds_dwordx4 v[134:135], off
	s_cmp_gt_u32 s41, 0xc00
	s_cbranch_scc1 .Lrst_p1_done
	v_lshlrev_b32_e32 v254, 6, v214
	v_add_u32_e32 v254, 0x21000, v254
	ds_read_b64 v[238:239], v254 offset:0
	ds_read_b64 v[252:253], v254 offset:8
	s_waitcnt lgkmcnt(0)
	v_add_f32_e32 v238, v238, v239
	v_add_f32_e32 v252, v252, v253
	v_add_f32_e32 v237, v238, v252
	ds_read_b64 v[238:239], v254 offset:16
	ds_read_b64 v[252:253], v254 offset:24
	s_waitcnt lgkmcnt(0)
	v_add_f32_e32 v238, v238, v239
	v_add_f32_e32 v252, v252, v253
	v_add_f32_e32 v233, v238, v252
	v_add_f32_e32 v237, v237, v233
; #define PG8_STAGE(bufoff, gbase, voff) do { _Pragma("unroll") for (int _i = 0; _i < 2; ++_i) \
;         __builtin_amdgcn_global_load_lds((const unsigned*)((const char*)(gbase) + (size_t)_i * r64 + (voff)), (PG8_LAS unsigned*)(lds + (bufoff) + ldsw + _i * 8192), 16, 0, 0); } while (0)
; #define PG8_LDA(dst, b, h) do { _Pragma("unroll") for (int m = 0; m < 4; ++m) _Pragma("unroll") for (int k = 0; k < 2; ++k) dst[m][k] = *(const PG8_LAS bf16x8*)(lds + PG8_SA(b, h) + aoff + m * 2048 + k * 1024); } while (0)
; #define PG8_LDB(dst, b, h) do { _Pragma("unroll") for (int n = 0; n < 2; ++n) _Pragma("unroll") for (int k = 0; k < 2; ++k) dst[n][k] = *(const PG8_LAS bf16x8*)(lds + PG8_SB(b, h) + boff + n * 2048 + k * 1024); } while (0)
; #define PG8_MMA(ai, bj, At, Bt) do { __builtin_amdgcn_s_setprio(1); _Pragma("unroll") for (int m = 0; m < 4; ++m) _Pragma("unroll") for (int n = 0; n < 2; ++n) _Pragma("unroll") for (int k = 0; k < 2; ++k) \
;         acc[ai][bj][m][n] = __builtin_amdgcn_mfma_f32_16x16x32_bf16(Bt[n][k], At[m][k], acc[ai][bj][m][n], 0, 0, 0); __builtin_amdgcn_s_setprio(0); } while (0)
; #define PG8_WAIT_V(n) asm volatile("s_waitcnt vmcnt(" #n ")" ::: "memory")
; #define PG8_WAIT_L(n) asm volatile("s_waitcnt lgkmcnt(" #n ")" ::: "memory")
; template <class Epi, class Sched, bool ALIGN_EPI = false, bool SP2 = false>
; __device__ __forceinline__ void gemm_phase(PG8_LAS unsigned char* lds, const Gemm g, const Sched& S, const Epi& E) {
;     ...
;             PG8_LDB(B0, 1, 0); PG8_LDB(B1, 1, 1); PG8_SCHED; PG8_LDA(At, 1, 0); PG8_STAGE(PG8_SA(0, 1), a2 + hstep, voffA);
;             PG8_WAIT_V(8); PG8_WAIT_L(0); PG8_BAR; PG8_MMA(0, 0, At, B0); PG8_MMA(0, 1, At, B1); PG8_BAR; PG8_SCHED;
;             PG8_LDA(At, 1, 1); PG8_STAGE(PG8_SB(1, 0), b3, voffB); PG8_STAGE(PG8_SB(1, 1), b3 + hstep, voffB); PG8_STAGE(PG8_SA(1, 0), a3, voffA);
;             PG8_WAIT_V(8); PG8_WAIT_L(0); PG8_BAR; PG8_MMA(1, 0, At, B0); PG8_MMA(1, 1, At, B1); PG8_BAR; PG8_SCHED;
; __device__ __forceinline__ float row_rs(const float* rsp, int row) {
;     const f32x4* q = (const f32x4*)(rsp + (size_t)row * 16);
;     const f32x4 a = q[0], b = q[1], c = q[2], d = q[3];
;     const float s = ((a[0] + a[1]) + (a[2] + a[3])) + ((b[0] + b[1]) + (b[2] + b[3])) + ((c[0] + c[1]) + (c[2] + c[3])) + ((d[0] + d[1]) + (d[2] + d[3]));
;     return rsqrtf(s * (1.0f / 1024.0f) + 1e-6f);
.Lrst_p1_done:
	s_waitcnt vmcnt(8)
	s_waitcnt lgkmcnt(0)
	s_barrier
	s_setprio 1
	s_waitcnt lgkmcnt(0)
	v_mfma_f32_16x16x32_bf16 v[134:137], v[26:29], v[74:77], v[190:193]
	v_mfma_f32_16x16x32_bf16 v[190:193], v[30:33], v[78:81], v[134:137]
	v_mfma_f32_16x16x32_bf16 v[134:137], v[66:69], v[74:77], v[186:189]
	v_mfma_f32_16x16x32_bf16 v[186:189], v[70:73], v[78:81], v[134:137]
	v_mfma_f32_16x16x32_bf16 v[134:137], v[26:29], v[102:105], v[174:177]
	v_mfma_f32_16x16x32_bf16 v[174:177], v[30:33], v[114:117], v[134:137]
	v_mfma_f32_16x16x32_bf16 v[134:137], v[66:69], v[102:105], v[170:173]
	v_mfma_f32_16x16x32_bf16 v[170:173], v[70:73], v[114:117], v[134:137]
	v_mfma_f32_16x16x32_bf16 v[134:137], v[26:29], v[118:121], v[158:161]
	v_mfma_f32_16x16x32_bf16 v[158:161], v[30:33], v[130:133], v[134:137]
	v_mfma_f32_16x16x32_bf16 v[134:137], v[66:69], v[118:121], v[154:157]
	v_mfma_f32_16x16x32_bf16 v[154:157], v[70:73], v[130:133], v[134:137]
	v_mfma_f32_16x16x32_bf16 v[134:137], v[26:29], v[210:213], v[142:145]
	v_mfma_f32_16x16x32_bf16 v[142:145], v[30:33], v[224:227], v[134:137]
	v_mfma_f32_16x16x32_bf16 v[134:137], v[66:69], v[210:213], v[138:141]
	v_mfma_f32_16x16x32_bf16 v[138:141], v[70:73], v[224:227], v[134:137]
	s_setprio 0
	s_setprio 1
	v_mfma_f32_16x16x32_bf16 v[34:37], v[202:205], v[74:77], v[34:37]
	v_mfma_f32_16x16x32_bf16 v[178:181], v[206:209], v[78:81], v[34:37]
	v_mfma_f32_16x16x32_bf16 v[34:37], v[194:197], v[102:105], v[38:41]
	v_mfma_f32_16x16x32_bf16 v[166:169], v[198:201], v[114:117], v[34:37]
	v_mfma_f32_16x16x32_bf16 v[34:37], v[202:205], v[102:105], v[42:45]
	v_mfma_f32_16x16x32_bf16 v[162:165], v[206:209], v[114:117], v[34:37]
	v_mfma_f32_16x16x32_bf16 v[34:37], v[194:197], v[118:121], v[46:49]
	v_mfma_f32_16x16x32_bf16 v[150:153], v[198:201], v[130:133], v[34:37]
	v_mfma_f32_16x16x32_bf16 v[34:37], v[202:205], v[118:121], v[50:53]
	v_mfma_f32_16x16x32_bf16 v[134:137], v[194:197], v[74:77], v[182:185]
	v_mfma_f32_16x16x32_bf16 v[146:149], v[206:209], v[130:133], v[34:37]
	v_mfma_f32_16x16x32_bf16 v[34:37], v[194:197], v[210:213], v[54:57]
	v_mfma_f32_16x16x32_bf16 v[182:185], v[198:201], v[78:81], v[134:137]
	v_mfma_f32_16x16x32_bf16 v[134:137], v[198:201], v[224:227], v[34:37]
	v_mfma_f32_16x16x32_bf16 v[34:37], v[202:205], v[210:213], v[58:61]
	v_mfma_f32_16x16x32_bf16 v[130:133], v[206:209], v[224:227], v[34:37]
	s_setprio 0
	s_barrier
	s_add_i32 s3, s3, s41
	v_lshl_add_u64 v[74:75], v[228:229], 0, s[34:35]
	s_mov_b32 m0, s3
	s_nop 1
	ds_read_b128 v[34:37], v243 offset:49152
	ds_read_b128 v[38:41], v243 offset:50176
	ds_read_b128 v[42:45], v243 offset:51200
	ds_read_b128 v[46:49], v243 offset:52224
	ds_read_b128 v[50:53], v243 offset:53248
	ds_read_b128 v[54:57], v243 offset:54272
	ds_read_b128 v[58:61], v243 offset:55296
	ds_read_b128 v[210:213], v243 offset:56320
	global_load_lds_dwordx4 v[74:75], off
	v_lshl_add_u64 v[74:75], v[230:231], 0, s[34:35]
	s_add_i32 m0, s3, 0x2000
	s_add_i32 s3, s13, s41
	global_load_lds_dwordx4 v[74:75], off
	v_lshl_add_u64 v[74:75], v[244:245], 0, s[34:35]
	s_mov_b32 m0, s3
	s_nop 0
	global_load_lds_dwordx4 v[74:75], off
	v_lshl_add_u64 v[74:75], v[246:247], 0, s[34:35]
	s_add_i32 m0, s3, 0x2000
	s_nop 0
	global_load_lds_dwordx4 v[74:75], off
	v_lshl_add_u64 v[74:75], v[248:249], 0, s[34:35]
	s_mov_b32 m0, s81
	s_nop 0
	global_load_lds_dwordx4 v[74:75], off
	v_lshl_add_u64 v[74:75], v[250:251], 0, s[34:35]
	s_mov_b32 m0, s1
	s_nop 0
	global_load_lds_dwordx4 v[74:75], off
	s_cmp_gt_u32 s41, 0xc00
	s_cbranch_scc1 .Lrst_p2_done
	ds_read_b64 v[238:239], v254 offset:32
	ds_read_b64 v[252:253], v254 offset:40
	s_waitcnt lgkmcnt(0)
	v_add_f32_e32 v238, v238, v239
	v_add_f32_e32 v252, v252, v253
	v_add_f32_e32 v233, v238, v252
	v_add_f32_e32 v237, v237, v233
	ds_read_b64 v[238:239], v254 offset:48
	ds_read_b64 v[252:253], v254 offset:56
	s_waitcnt lgkmcnt(0)
	v_add_f32_e32 v238, v238, v239
	v_add_f32_e32 v252, v252, v253
	v_add_f32_e32 v233, v238, v252
	v_add_f32_e32 v237, v237, v233
	v_fmamk_f32 v237, v237, 0x3a800000, v215
	v_lshlrev_b32_e32 v254, 2, v214
	v_cmp_gt_f32_e32 vcc, 0x800000, v237
	v_mul_f32_e32 v233, 0x4b800000, v237
	v_add_u32_e32 v254, 0x20100, v254
	v_cndmask_b32_e32 v237, v237, v233, vcc
	v_rsq_f32_e32 v237, v237
	s_nop 0
	v_mul_f32_e32 v233, 0x45800000, v237
	v_cndmask_b32_e32 v237, v237, v233, vcc
	ds_write_b32 v254, v237
.Lrst_p2_done:
	s_waitcnt vmcnt(8)
	s_waitcnt lgkmcnt(0)
	s_barrier
	s_setprio 1
	s_waitcnt lgkmcnt(0)
	v_mfma_f32_16x16x32_bf16 v[74:77], v[26:29], v[34:37], v[126:129]
	v_mfma_f32_16x16x32_bf16 v[126:129], v[30:33], v[38:41], v[74:77]
	v_mfma_f32_16x16x32_bf16 v[74:77], v[66:69], v[34:37], v[122:125]
	v_mfma_f32_16x16x32_bf16 v[122:125], v[70:73], v[38:41], v[74:77]
	v_mfma_f32_16x16x32_bf16 v[74:77], v[26:29], v[42:45], v[110:113]
	v_mfma_f32_16x16x32_bf16 v[110:113], v[30:33], v[46:49], v[74:77]
	v_mfma_f32_16x16x32_bf16 v[74:77], v[66:69], v[42:45], v[106:109]
	v_mfma_f32_16x16x32_bf16 v[106:109], v[70:73], v[46:49], v[74:77]
	v_mfma_f32_16x16x32_bf16 v[74:77], v[26:29], v[50:53], v[94:97]
	v_mfma_f32_16x16x32_bf16 v[2:5], v[26:29], v[58:61], v[2:5]
	v_mfma_f32_16x16x32_bf16 v[94:97], v[30:33], v[54:57], v[74:77]
	v_mfma_f32_16x16x32_bf16 v[74:77], v[66:69], v[50:53], v[90:93]
	v_mfma_f32_16x16x32_bf16 v[78:81], v[30:33], v[210:213], v[2:5]
	v_mfma_f32_16x16x32_bf16 v[2:5], v[66:69], v[58:61], v[6:9]
	v_mfma_f32_16x16x32_bf16 v[90:93], v[70:73], v[54:57], v[74:77]
	v_mfma_f32_16x16x32_bf16 v[74:77], v[70:73], v[210:213], v[2:5]
	s_setprio 0
	s_setprio 1
	v_mfma_f32_16x16x32_bf16 v[2:5], v[194:197], v[34:37], v[10:13]
	v_mfma_f32_16x16x32_bf16 v[118:121], v[198:201], v[38:41], v[2:5]
	v_mfma_f32_16x16x32_bf16 v[2:5], v[202:205], v[34:37], v[14:17]
	v_mfma_f32_16x16x32_bf16 v[114:117], v[206:209], v[38:41], v[2:5]
	v_mfma_f32_16x16x32_bf16 v[2:5], v[194:197], v[42:45], v[62:65]
	v_mfma_f32_16x16x32_bf16 v[102:105], v[198:201], v[46:49], v[2:5]
	v_mfma_f32_16x16x32_bf16 v[2:5], v[202:205], v[42:45], v[98:101]
	v_mfma_f32_16x16x32_bf16 v[98:101], v[206:209], v[46:49], v[2:5]
	v_mfma_f32_16x16x32_bf16 v[2:5], v[194:197], v[50:53], v[86:89]
	v_mfma_f32_16x16x32_bf16 v[86:89], v[198:201], v[54:57], v[2:5]
	v_mfma_f32_16x16x32_bf16 v[2:5], v[202:205], v[50:53], v[82:85]
	v_mfma_f32_16x16x32_bf16 v[82:85], v[206:209], v[54:57], v[2:5]
	v_mfma_f32_16x16x32_bf16 v[2:5], v[194:197], v[58:61], v[18:21]
	v_mfma_f32_16x16x32_bf16 v[70:73], v[198:201], v[210:213], v[2:5]
	v_mfma_f32_16x16x32_bf16 v[2:5], v[202:205], v[58:61], v[22:25]
	v_mfma_f32_16x16x32_bf16 v[66:69], v[206:209], v[210:213], v[2:5]
	s_setprio 0
	s_barrier
	s_add_u32 s6, s6, 0x100
	s_addc_u32 s7, s7, 0
	s_add_u32 s10, s10, 0x100
	s_addc_u32 s11, s11, 0
	s_cmp_ge_u32 s12, s2
	s_mov_b32 s8, s12
	s_cbranch_scc1 .Lkloop_done

; #define LAS __attribute__((address_space(3)))
; __device__ __forceinline__ int opaque_tid() { int t = threadIdx.x; asm volatile("" : "+v"(t)); return t; }
; __device__ __forceinline__ void attention_phase(PPtr p, int layer, LAS unsigned char* L, unsigned* counter, const bool do_store) {
;     const int tid = opaque_tid(), lane = tid & 63, wave = tid >> 6, r = lane & 31, h = lane >> 5;
;     unsigned char* big = p->ws + WS_BIG;
;     LAS float* lut = (LAS float*)(L + AL_LUT);
;     LAS float* cb = (LAS float*)(L + AL_CB);
;     LAS float* scan = (LAS float*)(L + AL_SCAN);
;     volatile LAS unsigned* itemw = (volatile LAS unsigned*)(L + AL_ITEM);
;     const float* rel = p->in[1];
;     for (;;) {
;         __syncthreads();
;         if (tid == 0) itemw[0] = atomicAdd(counter, 1u);
;         __syncthreads();
;         const int idx = (int)itemw[0];
;         if (idx >= N_ATT_ITEMS) break;
;         int tl_ = tid; asm volatile("" : "+v"(tl_));
;         const int lane = tl_ & 63, r = lane & 31, h = lane >> 5;
.LBB0_494:
	s_and_b64 vcc, exec, s[6:7]
	s_cbranch_vccz .LBB0_690
	s_load_dwordx4 s[24:27], s[42:43], 0xb0
	s_lshl_b32 s1, s16, 2
	v_mov_b32_e32 v190, v214
	v_mov_b32_e32 v237, 0x80
	v_mov_b32_e32 v238, 0xff800000
	v_mov_b32_e32 v239, 0x7f800000
	s_load_dwordx2 s[46:47], s[42:43], 0x8
	s_waitcnt lgkmcnt(0)
	s_add_u32 s22, s26, s1
	s_addc_u32 s23, s27, 0
	s_lshl_b32 s66, s16, 6
	s_add_i32 s67, 0, 0x12000
	s_add_u32 s2, s26, 0x1b200000
	v_writelane_b32 v255, s2, 34
	s_addc_u32 s2, s27, 0
	v_writelane_b32 v255, s2, 32
	s_add_u32 s2, s26, 0x1ca00000
	v_writelane_b32 v255, s2, 36
	s_addc_u32 s2, s27, 0
	v_writelane_b32 v255, s2, 41
	s_add_u32 s2, s26, 0x1e200000
	v_writelane_b32 v255, s2, 42
	s_addc_u32 s2, s27, 0
	s_waitcnt vmcnt(0)
	v_lshlrev_b32_e32 v2, 3, v190
	v_writelane_b32 v255, s2, 44
	v_ashrrev_i32_e32 v196, 3, v190
	v_and_b32_e32 v156, 56, v2
	s_movk_i32 s2, 0x48
	v_bfe_u32 v5, v190, 5, 1
	v_mad_u64_u32 v[2:3], s[2:3], v196, s2, v[156:157]
	v_and_b32_e32 v194, 31, v190
	v_lshlrev_b32_e32 v198, 2, v5
	v_lshrrev_b32_e32 v3, 2, v190
	s_add_u32 s2, s26, 0x100000
	v_lshlrev_b32_e32 v0, 2, v190
	v_lshlrev_b32_e32 v195, 3, v5
	v_lshl_add_u32 v197, v2, 1, 0
	v_mul_u32_u24_e32 v2, 0x48, v194
	v_and_b32_e32 v6, 16, v190
	v_and_or_b32 v3, v3, 3, v198
	v_writelane_b32 v255, s2, 49
	s_addc_u32 s2, s27, 0
	v_ashrrev_i32_e32 v191, 6, v190
	v_and_or_b32 v6, v0, 12, v6
	v_add_lshl_u32 v199, v195, v2, 1
	v_mul_u32_u24_e32 v2, 0x48, v3
	v_writelane_b32 v255, s2, 47
	v_add_lshl_u32 v200, v2, v6, 1
	v_lshlrev_b32_e32 v2, 2, v191
	v_readlane_b32 s2, v255, 12
	v_lshlrev_b32_e32 v204, 4, v5
	v_cmp_lt_u32_e32 vcc, 18, v190
	v_add_u32_e32 v202, s2, v2
	v_cmp_lt_i32_e64 s[2:3], 0, v191
	v_and_b32_e32 v4, 63, v190
	v_cmp_eq_u32_e64 s[10:11], 0, v4
	v_writelane_b32 v255, s2, 37
	v_cmp_gt_u32_e64 s[12:13], 32, v4
	v_lshlrev_b32_e32 v192, 5, v191
	v_writelane_b32 v255, s3, 38
	s_add_u32 s2, s26, 0xea00000
	v_writelane_b32 v255, s2, 45
	s_addc_u32 s2, s27, 0
	s_add_u32 s77, s26, 0x18200000
	v_writelane_b32 v255, s2, 30
	s_addc_u32 s2, s27, 0
	v_writelane_b32 v255, s2, 39
	s_movk_i32 s2, 0x90
	v_mad_u32_u24 v206, v194, s2, v204
	v_readlane_b32 s2, v255, 13
	s_add_u32 s38, s26, 0x19a00000
	s_addc_u32 s81, s27, 0
	v_add_u32_e32 v209, s2, v2
	v_cndmask_b32_e64 v2, 16, 17, vcc
	v_cmp_lt_u32_e32 vcc, 20, v190
	s_movk_i32 s2, 0x42
	s_add_u32 s82, s26, 0xd200000
	v_cndmask_b32_e64 v4, 0, 1, vcc
	v_cmp_lt_u32_e32 vcc, 23, v190
	s_addc_u32 s83, s27, 0
	s_add_u32 s84, s26, 0x15200000
	v_addc_co_u32_e32 v2, vcc, v2, v4, vcc
	v_cmp_lt_u32_e32 vcc, 26, v190
	s_addc_u32 s85, s27, 0
	s_add_u32 s86, s26, 0x16a00000
	v_cndmask_b32_e64 v4, 0, 1, vcc
	v_cmp_lt_u32_e32 vcc, 30, v190
	s_addc_u32 s87, s27, 0
	s_lshl_b64 s[48:49], s[16:17], 10
	v_addc_co_u32_e32 v2, vcc, v2, v4, vcc
	v_cmp_lt_u32_e32 vcc, 34, v190
	s_add_u32 s50, s42, s1
	s_addc_u32 s51, s43, 0
	v_cndmask_b32_e64 v4, 0, 1, vcc
	v_cmp_lt_u32_e32 vcc, 39, v190
	s_add_u32 s90, s26, 0x11200000
	s_addc_u32 s91, s27, 0
	v_addc_co_u32_e32 v2, vcc, v2, v4, vcc
	v_cmp_lt_u32_e32 vcc, 45, v190
	v_readlane_b32 s1, v255, 14
	v_mul_u32_u24_e32 v3, 0x88, v3
	v_cndmask_b32_e64 v4, 0, 1, vcc
	v_cmp_lt_u32_e32 vcc, 51, v190
	s_add_u32 s92, s26, 0x13200000
	v_add_u32_e32 v210, s1, v0
	v_addc_co_u32_e32 v2, vcc, v2, v4, vcc
	v_cmp_lt_u32_e32 vcc, 58, v190
	s_movk_i32 s1, 0x88
	v_add_lshl_u32 v3, v3, v6, 1
	v_cndmask_b32_e64 v4, 0, 1, vcc
	v_cmp_lt_u32_e32 vcc, s2, v190
	s_movk_i32 s2, 0x4c
	v_add_u32_e32 v193, s67, v0
	v_addc_co_u32_e32 v2, vcc, v2, v4, vcc
	v_cmp_lt_u32_e32 vcc, s2, v190
	s_movk_i32 s2, 0x56
	v_lshlrev_b32_e32 v7, 4, v190
	v_cndmask_b32_e64 v4, 0, 1, vcc
	v_cmp_lt_u32_e32 vcc, s2, v190
	s_movk_i32 s2, 0x62
	s_addc_u32 s93, s27, 0
	v_addc_co_u32_e32 v2, vcc, v2, v4, vcc
	v_cmp_lt_u32_e32 vcc, s2, v190
	s_movk_i32 s2, 0x70
	v_lshlrev_b32_e32 v211, 9, v196
	v_cndmask_b32_e64 v4, 0, 1, vcc
	v_cmp_lt_u32_e32 vcc, s2, v190
	v_mul_lo_u32 v0, v196, s1
	v_add_u32_e32 v213, 0, v3
	v_addc_co_u32_e32 v2, vcc, v2, v4, vcc
	v_cmp_gt_i32_e32 vcc, 16, v190
	v_add_u32_e32 v216, 0x2200, v3
	v_add_u32_e32 v217, 0x3300, v3
	v_cndmask_b32_e32 v2, v2, v190, vcc
	v_mul_lo_u32 v218, v2, 10
	v_or_b32_e32 v2, v192, v194
	s_lshl_b64 s[52:53], s[16:17], 9
	v_sub_u32_e32 v2, v2, v198
	v_mul_lo_u32 v3, v196, s89
	v_add_lshl_u32 v0, v156, v0, 1
	s_add_u32 s94, s24, 0x3000000
	v_subrev_u32_e32 v220, 59, v2
	v_or_b32_e32 v3, v3, v156
	v_add_u32_e32 v223, 0xffffff25, v2
	v_add_u32_e32 v225, 0xffffff3f, v2
	v_or_b32_e32 v226, v211, v156
	v_add_u32_e32 v2, 0, v7
	v_cmp_eq_u32_e64 s[4:5], 0, v190
	v_cmp_gt_i32_e64 s[6:7], s0, v190
	v_add_u32_e32 v201, 0x1200, v200
	v_or_b32_e32 v203, 0xffffa000, v156
	v_mul_u32_u24_e32 v205, 0x90, v194
	v_or_b32_e32 v207, 0xffff4000, v156
	v_or_b32_e32 v208, 0xfffee000, v156
	v_or_b32_e32 v212, 0xffff8000, v156
	s_addc_u32 s95, s25, 0
	v_add_u32_e32 v219, 0xffffff40, v196
	v_add_u32_e32 v221, 0xffffff80, v196
	v_add_u32_e32 v222, 0xc000, v3
	v_add_u32_e32 v224, 0x12000, v3
	v_add_u32_e32 v227, 0x8000, v226
	v_add_u32_e32 v228, 0x12800, v2
	v_add_u32_e32 v229, 0, v0
	s_and_saveexec_b64 s[14:15], s[4:5]
	s_cbranch_execz .Latt_pf0
	v_mov_b32_e32 v252, 1
	global_atomic_add v252, v1, v252, s[22:23] sc0
